# attention waves 4-7: priority tapers inside the P.V section (2, then 1 after 16 MFMAs, 0 after 24) and inside QK^T (1, then 0 after 10 MFMAs)
# speedup vs baseline: 1.0006x; 1.0006x over previous
; #define SBAR() __builtin_amdgcn_sched_barrier(0)
; #define PV_LOAD(S, DD) do { S[0] = tr_read<v_off8(DD, 0, 0)>(vb); S[1] = tr_read<v_off8(DD, 0, 1)>(vb); S[2] = tr_read<v_off8(DD, 1, 0)>(vb); S[3] = tr_read<v_off8(DD, 1, 1)>(vb); \
;     S[4] = tr_read<v_off8(DD, 2, 0)>(vb); S[5] = tr_read<v_off8(DD, 2, 1)>(vb); S[6] = tr_read<v_off8(DD, 3, 0)>(vb); S[7] = tr_read<v_off8(DD, 3, 1)>(vb); } while (0)
; #define PV_MMA(OD, S) do { OD = __builtin_amdgcn_mfma_f32_32x32x16_bf16(pa0, PV_PK(S[0], S[1]), OD, 0, 0, 0); OD = __builtin_amdgcn_mfma_f32_32x32x16_bf16(pa1, PV_PK(S[2], S[3]), OD, 0, 0, 0); \
;     OD = __builtin_amdgcn_mfma_f32_32x32x16_bf16(pa2, PV_PK(S[4], S[5]), OD, 0, 0, 0); OD = __builtin_amdgcn_mfma_f32_32x32x16_bf16(pa3, PV_PK(S[6], S[7]), OD, 0, 0, 0); } while (0)
; #define PV_W8() do { asm volatile("s_waitcnt lgkmcnt(8)" ::: "memory"); SBAR(); } while (0)
; #define PV_W0() do { asm volatile("s_waitcnt lgkmcnt(0)" ::: "memory"); SBAR(); } while (0)
; __device__ __forceinline__ void pv8(f32x16* o, int vb, bf16x8 pa0, bf16x8 pa1, bf16x8 pa2, bf16x8 pa3) {
;   s16x4 A[8], B[8];
;   PV_LOAD(A, 0);
;   PV_LOAD(B, 1); PV_W8(); PV_MMA(o[0], A); SBAR();
;   PV_LOAD(A, 2); PV_W8(); PV_MMA(o[1], B); SBAR();
;   PV_LOAD(B, 3); PV_W8(); PV_MMA(o[2], A); SBAR();
;   PV_LOAD(A, 4); PV_W8(); PV_MMA(o[3], B); SBAR();
;   PV_LOAD(B, 5); PV_W8(); PV_MMA(o[4], A); SBAR();
;   PV_LOAD(A, 6); PV_W8(); PV_MMA(o[5], B); SBAR();
;   PV_LOAD(B, 7); PV_W8(); PV_MMA(o[6], A); SBAR();
;   PV_W0(); PV_MMA(o[7], B);
; }
; __device__ __forceinline__ void attn_pass(const bf16_t* __restrict__ Qb, const bf16_t* __restrict__ Kh, const bf16_t* __restrict__ Vh,
;                                           float* Ob, int mode, float lam, int qpos0, int seq, char* lds, const int wv, bf16_t* OBh) {
;     ...
;       __builtin_amdgcn_s_setprio(1);
;       pv8(o, vb0 + bprev, pa0, pa1, pa2, pa3);
;       SBAR();
;       { const int k0 = j * KVBLK; qkt(p0, p1, lds + bcur, qr, r32, hi, tab, k0 - qlane, FARMODE(k0)); }
;       __builtin_amdgcn_s_setprio(0);
.LBB0_113:
	s_setprio 2
	v_add_u32_e32 v160, s8, v226
	ds_read_b64_tr_b16 v[144:145], v160 offset:0
	ds_read_b64_tr_b16 v[146:147], v160 offset:0x800
	ds_read_b64_tr_b16 v[148:149], v160 offset:0x1000
	ds_read_b64_tr_b16 v[150:151], v160 offset:0x1800
	ds_read_b64_tr_b16 v[152:153], v160 offset:0x2000
	ds_read_b64_tr_b16 v[154:155], v160 offset:0x2800
	ds_read_b64_tr_b16 v[156:157], v160 offset:0x3000
	ds_read_b64_tr_b16 v[158:159], v160 offset:0x3800
	ds_read_b64_tr_b16 v[194:195], v160 offset:0x200
	ds_read_b64_tr_b16 v[196:197], v160 offset:0xa00
	ds_read_b64_tr_b16 v[198:199], v160 offset:0x1200
	ds_read_b64_tr_b16 v[200:201], v160 offset:0x1a00
	ds_read_b64_tr_b16 v[202:203], v160 offset:0x2200
	ds_read_b64_tr_b16 v[204:205], v160 offset:0x2a00
	ds_read_b64_tr_b16 v[206:207], v160 offset:0x3200
	ds_read_b64_tr_b16 v[208:209], v160 offset:0x3a00
	s_waitcnt lgkmcnt(8)
	s_nop 0
	v_mfma_f32_32x32x16_bf16 v[96:111], v[128:131], v[144:147], v[96:111]
	v_mfma_f32_32x32x16_bf16 v[96:111], v[132:135], v[148:151], v[96:111]
	v_mfma_f32_32x32x16_bf16 v[96:111], v[136:139], v[152:155], v[96:111]
	v_mfma_f32_32x32x16_bf16 v[96:111], v[140:143], v[156:159], v[96:111]
	ds_read_b64_tr_b16 v[144:145], v160 offset:0x400
	ds_read_b64_tr_b16 v[146:147], v160 offset:0xc00
	ds_read_b64_tr_b16 v[148:149], v160 offset:0x1400
	ds_read_b64_tr_b16 v[150:151], v160 offset:0x1c00
	ds_read_b64_tr_b16 v[152:153], v160 offset:0x2400
	ds_read_b64_tr_b16 v[154:155], v160 offset:0x2c00
	ds_read_b64_tr_b16 v[156:157], v160 offset:0x3400
	ds_read_b64_tr_b16 v[158:159], v160 offset:0x3c00
	s_waitcnt lgkmcnt(8)
	v_mfma_f32_32x32x16_bf16 v[112:127], v[128:131], v[194:197], v[112:127]
	v_mfma_f32_32x32x16_bf16 v[112:127], v[132:135], v[198:201], v[112:127]
	v_mfma_f32_32x32x16_bf16 v[112:127], v[136:139], v[202:205], v[112:127]
	v_mfma_f32_32x32x16_bf16 v[112:127], v[140:143], v[206:209], v[112:127]
	ds_read_b64_tr_b16 v[194:195], v160 offset:0x600
	ds_read_b64_tr_b16 v[196:197], v160 offset:0xe00
	ds_read_b64_tr_b16 v[198:199], v160 offset:0x1600
	ds_read_b64_tr_b16 v[200:201], v160 offset:0x1e00
	ds_read_b64_tr_b16 v[202:203], v160 offset:0x2600
	ds_read_b64_tr_b16 v[204:205], v160 offset:0x2e00
	ds_read_b64_tr_b16 v[206:207], v160 offset:0x3600
	ds_read_b64_tr_b16 v[208:209], v160 offset:0x3e00
	s_waitcnt lgkmcnt(8)
	v_mfma_f32_32x32x16_bf16 v[80:95], v[128:131], v[144:147], v[80:95]
	v_mfma_f32_32x32x16_bf16 v[80:95], v[132:135], v[148:151], v[80:95]
	v_mfma_f32_32x32x16_bf16 v[80:95], v[136:139], v[152:155], v[80:95]
	v_mfma_f32_32x32x16_bf16 v[80:95], v[140:143], v[156:159], v[80:95]
	ds_read_b64_tr_b16 v[144:145], v160 offset:0x4000
	ds_read_b64_tr_b16 v[146:147], v160 offset:0x4800
	ds_read_b64_tr_b16 v[148:149], v160 offset:0x5000
	ds_read_b64_tr_b16 v[150:151], v160 offset:0x5800
	ds_read_b64_tr_b16 v[152:153], v160 offset:0x6000
	ds_read_b64_tr_b16 v[154:155], v160 offset:0x6800
	ds_read_b64_tr_b16 v[156:157], v160 offset:0x7000
	ds_read_b64_tr_b16 v[158:159], v160 offset:0x7800
	s_waitcnt lgkmcnt(8)
	v_mfma_f32_32x32x16_bf16 v[64:79], v[128:131], v[194:197], v[64:79]
	v_mfma_f32_32x32x16_bf16 v[64:79], v[132:135], v[198:201], v[64:79]
	v_mfma_f32_32x32x16_bf16 v[64:79], v[136:139], v[202:205], v[64:79]
	v_mfma_f32_32x32x16_bf16 v[64:79], v[140:143], v[206:209], v[64:79]
	ds_read_b64_tr_b16 v[194:195], v160 offset:0x4200
	ds_read_b64_tr_b16 v[196:197], v160 offset:0x4a00
	ds_read_b64_tr_b16 v[198:199], v160 offset:0x5200
	ds_read_b64_tr_b16 v[200:201], v160 offset:0x5a00
	ds_read_b64_tr_b16 v[202:203], v160 offset:0x6200
	ds_read_b64_tr_b16 v[204:205], v160 offset:0x6a00
	ds_read_b64_tr_b16 v[206:207], v160 offset:0x7200
	ds_read_b64_tr_b16 v[208:209], v160 offset:0x7a00
	s_waitcnt lgkmcnt(8)
	s_setprio 1
	v_mfma_f32_32x32x16_bf16 v[48:63], v[128:131], v[144:147], v[48:63]
	v_mfma_f32_32x32x16_bf16 v[48:63], v[132:135], v[148:151], v[48:63]
	v_mfma_f32_32x32x16_bf16 v[48:63], v[136:139], v[152:155], v[48:63]
	v_mfma_f32_32x32x16_bf16 v[48:63], v[140:143], v[156:159], v[48:63]
	ds_read_b64_tr_b16 v[144:145], v160 offset:0x4400
	ds_read_b64_tr_b16 v[146:147], v160 offset:0x4c00
	ds_read_b64_tr_b16 v[148:149], v160 offset:0x5400
	ds_read_b64_tr_b16 v[150:151], v160 offset:0x5c00
	ds_read_b64_tr_b16 v[152:153], v160 offset:0x6400
	ds_read_b64_tr_b16 v[154:155], v160 offset:0x6c00
	ds_read_b64_tr_b16 v[156:157], v160 offset:0x7400
	ds_read_b64_tr_b16 v[158:159], v160 offset:0x7c00
	s_waitcnt lgkmcnt(8)
	v_mfma_f32_32x32x16_bf16 v[32:47], v[128:131], v[194:197], v[32:47]
	v_mfma_f32_32x32x16_bf16 v[32:47], v[132:135], v[198:201], v[32:47]
	v_mfma_f32_32x32x16_bf16 v[32:47], v[136:139], v[202:205], v[32:47]
	v_mfma_f32_32x32x16_bf16 v[32:47], v[140:143], v[206:209], v[32:47]
	ds_read_b64_tr_b16 v[194:195], v160 offset:0x4600
	ds_read_b64_tr_b16 v[196:197], v160 offset:0x4e00
	ds_read_b64_tr_b16 v[198:199], v160 offset:0x5600
	ds_read_b64_tr_b16 v[200:201], v160 offset:0x5e00
	ds_read_b64_tr_b16 v[202:203], v160 offset:0x6600
	ds_read_b64_tr_b16 v[204:205], v160 offset:0x6e00
	ds_read_b64_tr_b16 v[206:207], v160 offset:0x7600
	ds_read_b64_tr_b16 v[208:209], v160 offset:0x7e00
	s_waitcnt lgkmcnt(8)
	s_setprio 0
	v_mfma_f32_32x32x16_bf16 v[16:31], v[128:131], v[144:147], v[16:31]
	v_mfma_f32_32x32x16_bf16 v[16:31], v[132:135], v[148:151], v[16:31]
	v_mfma_f32_32x32x16_bf16 v[16:31], v[136:139], v[152:155], v[16:31]
	v_mfma_f32_32x32x16_bf16 v[16:31], v[140:143], v[156:159], v[16:31]
	s_waitcnt lgkmcnt(0)
	v_mfma_f32_32x32x16_bf16 v[0:15], v[128:131], v[194:197], v[0:15]
	v_mfma_f32_32x32x16_bf16 v[0:15], v[132:135], v[198:201], v[0:15]
	v_mfma_f32_32x32x16_bf16 v[0:15], v[136:139], v[202:205], v[0:15]
	v_mfma_f32_32x32x16_bf16 v[0:15], v[140:143], v[206:209], v[0:15]
	s_setprio 1
	s_cmpk_lt_u32 s77, 0x113
	s_cbranch_scc1 .LBB0_115
	s_add_i32 s8, s77, 0xffffff67
	s_cmpk_gt_i32 s8, 0xff66
	s_cselect_b32 s8, 0x600, 0
	s_add_i32 s8, s8, 0
	s_add_i32 s8, s8, 0x24800
	v_mov_b32_e32 v128, s8
	ds_read_b32 v160, v128
	s_mov_b32 s32, 1
	s_waitcnt lgkmcnt(0)
	v_mul_f32_e32 v128, 0x3fb8aa3b, v160
	v_readfirstlane_b32 s99, v160
	v_readfirstlane_b32 s98, v128
	s_branch .LBB0_118

; __device__ __forceinline__ void partialSM(f32x16& p0, f32x16& p1, float& m_reg, float& mn, float& alpha) {
;   constexpr float C = LOG2E;
;   float pmax = p0[0];
; #pragma unroll
;   for (int r = 1; r < 16; ++r) pmax = fmaxf(pmax, p0[r]);
; #pragma unroll
;   for (int r = 0; r < 16; ++r) pmax = fmaxf(pmax, p1[r]);
;   { auto rr = __builtin_amdgcn_permlane32_swap(__float_as_uint(pmax), __float_as_uint(pmax), false, false);
;     pmax = fmaxf(__uint_as_float(rr[0]), __uint_as_float(rr[1])); }
;   if (__builtin_expect(__all(pmax - m_reg <= THR), 1)) { mn = m_reg; alpha = 1.f; }
;   else { mn = fmaxf(m_reg, pmax); alpha = __builtin_amdgcn_exp2f((m_reg - mn) * C); m_reg = mn; }
; __device__ __forceinline__ void qkt(f32x16& p0, f32x16& p1, const char* Ks, const bf16x8* qr, int r32, int hi, const LAS float* tab, int rel0, int farmode) {
;     ...
;   for (int d0 = 0; d0 < 8; ++d0) { int cb = (d0 * 16 + hi * 8) * 2;
;     bf16x8 b0 = *reinterpret_cast<const bf16x8*>(Ks + KSWZ(r32, cb));
;     bf16x8 b1 = *reinterpret_cast<const bf16x8*>(Ks + KSWZ(32 + r32, cb));
;     p0 = __builtin_amdgcn_mfma_f32_32x32x16_bf16(b0, qr[d0], p0, 0, 0, 0);
;     p1 = __builtin_amdgcn_mfma_f32_32x32x16_bf16(b1, qr[d0], p1, 0, 0, 0); }
.Lc0B_join:
	ds_read_b128 v[198:201], v160 offset:8192
	v_add3_u32 v160, s8, v239, v235
	s_waitcnt lgkmcnt(3)
	v_mfma_f32_32x32x16_bf16 v[144:159], v[202:205], v[166:169], v[144:159]
	ds_read_b128 v[202:205], v160
	s_waitcnt lgkmcnt(3)
	v_mfma_f32_32x32x16_bf16 v[128:143], v[206:209], v[166:169], v[128:143]
	ds_read_b128 v[206:209], v160 offset:8192
	v_add3_u32 v160, s8, v240, v235
	s_waitcnt lgkmcnt(3)
	v_mfma_f32_32x32x16_bf16 v[144:159], v[194:197], v[170:173], v[144:159]
	ds_read_b128 v[194:197], v160
	s_waitcnt lgkmcnt(3)
	v_mfma_f32_32x32x16_bf16 v[128:143], v[198:201], v[170:173], v[128:143]
	ds_read_b128 v[198:201], v160 offset:8192
	v_add3_u32 v160, s8, v241, v235
	s_waitcnt lgkmcnt(3)
	v_mfma_f32_32x32x16_bf16 v[144:159], v[202:205], v[174:177], v[144:159]
	ds_read_b128 v[202:205], v160
	s_waitcnt lgkmcnt(3)
	v_mfma_f32_32x32x16_bf16 v[128:143], v[206:209], v[174:177], v[128:143]
	ds_read_b128 v[206:209], v160 offset:8192
	v_add3_u32 v160, s8, v242, v235
	s_waitcnt lgkmcnt(3)
	v_mfma_f32_32x32x16_bf16 v[144:159], v[194:197], v[178:181], v[144:159]
	ds_read_b128 v[194:197], v160
	s_waitcnt lgkmcnt(3)
	v_mfma_f32_32x32x16_bf16 v[128:143], v[198:201], v[178:181], v[128:143]
	ds_read_b128 v[198:201], v160 offset:8192
	v_add3_u32 v160, s8, v243, v235
	s_waitcnt lgkmcnt(3)
	s_setprio 0
	v_mfma_f32_32x32x16_bf16 v[144:159], v[202:205], v[182:185], v[144:159]
	ds_read_b128 v[202:205], v160
	s_waitcnt lgkmcnt(3)
	v_mfma_f32_32x32x16_bf16 v[128:143], v[206:209], v[182:185], v[128:143]
	ds_read_b128 v[206:209], v160 offset:8192
	s_waitcnt lgkmcnt(3)
	v_mfma_f32_32x32x16_bf16 v[144:159], v[194:197], v[186:189], v[144:159]
	s_waitcnt lgkmcnt(2)
	v_mfma_f32_32x32x16_bf16 v[128:143], v[198:201], v[186:189], v[128:143]
	s_waitcnt lgkmcnt(1)
	v_mfma_f32_32x32x16_bf16 v[144:159], v[202:205], v[190:193], v[144:159]
	s_waitcnt lgkmcnt(0)
	v_mfma_f32_32x32x16_bf16 v[128:143], v[206:209], v[190:193], v[128:143]
	s_setprio 0
	s_nop 9
	v_max_f32_e32 v160, v145, v145
	v_max_f32_e32 v194, v144, v144
	v_max_f32_e32 v160, v194, v160
	v_max3_f32 v160, v160, v146, v147
	v_max3_f32 v160, v160, v148, v149
	v_max3_f32 v160, v160, v150, v151
	v_max3_f32 v160, v160, v152, v153
	v_max3_f32 v160, v160, v154, v155
	v_max3_f32 v160, v160, v156, v157
	v_max3_f32 v160, v160, v158, v159
	v_max3_f32 v160, v160, v128, v129
	v_max3_f32 v160, v160, v130, v131
	v_max3_f32 v160, v160, v132, v133
	v_max3_f32 v160, v160, v134, v135
	v_max3_f32 v160, v160, v136, v137
	v_max3_f32 v160, v160, v138, v139
	v_max3_f32 v160, v160, v140, v141
	v_max3_f32 v160, v160, v142, v143
	v_mov_b32_e32 v194, v160
	s_nop 1
	v_permlane32_swap_b32_e32 v160, v194
	v_max_f32_e32 v194, v194, v194
	v_max_f32_e32 v160, v160, v160
	v_max_f32_e32 v160, v160, v194
	v_add_f32_e32 v160, s99, v160
	v_sub_f32_e32 v194, v160, v250
	v_cmp_ge_f32_e32 vcc, s53, v194
	v_max_f32_e32 v194, v250, v250
	v_max_f32_e32 v253, v194, v160
	v_sub_f32_e32 v160, v250, v253
	v_mul_f32_e32 v160, 0x3fb8aa3b, v160
	v_exp_f32_e32 v160, v160
	s_cmp_eq_u64 vcc, exec
	s_cselect_b64 s[8:9], -1, 0
	v_cndmask_b32_e64 v160, v160, 1.0, s[8:9]
	v_cmp_gt_f32_e32 vcc, 1.0, v160
	s_cbranch_vccz .LBB0_122
	s_and_saveexec_b64 s[10:11], s[6:7]
	v_lshl_add_u32 v194, v213, 2, s80
	ds_write_b32 v194, v160 offset:128
	s_or_b64 exec, exec, s[10:11]
	s_waitcnt lgkmcnt(0)
	v_add_u32_e32 v194, s80, v234
	ds_read_b128 v[206:209], v194 offset:224
	ds_read_b128 v[202:205], v194 offset:192
	ds_read_b128 v[198:201], v194 offset:160
	ds_read_b128 v[194:197], v194 offset:128
	s_waitcnt lgkmcnt(0)
	v_pk_mul_f32 v[108:109], v[108:109], v[206:207]
	v_pk_mul_f32 v[104:105], v[104:105], v[202:203]
	v_pk_mul_f32 v[100:101], v[100:101], v[198:199]
	v_pk_mul_f32 v[110:111], v[110:111], v[208:209]
	v_pk_mul_f32 v[106:107], v[106:107], v[204:205]
	v_pk_mul_f32 v[102:103], v[102:103], v[200:201]
	v_pk_mul_f32 v[98:99], v[98:99], v[196:197]
	v_pk_mul_f32 v[96:97], v[96:97], v[194:195]
	v_pk_mul_f32 v[124:125], v[124:125], v[206:207]
	v_pk_mul_f32 v[120:121], v[120:121], v[202:203]
	v_pk_mul_f32 v[116:117], v[116:117], v[198:199]
	v_pk_mul_f32 v[126:127], v[126:127], v[208:209]
	v_pk_mul_f32 v[122:123], v[122:123], v[204:205]
	v_pk_mul_f32 v[118:119], v[118:119], v[200:201]
	v_pk_mul_f32 v[114:115], v[114:115], v[196:197]
	v_pk_mul_f32 v[112:113], v[112:113], v[194:195]
	v_pk_mul_f32 v[92:93], v[92:93], v[206:207]
	v_pk_mul_f32 v[88:89], v[88:89], v[202:203]
	v_pk_mul_f32 v[84:85], v[84:85], v[198:199]
	v_pk_mul_f32 v[94:95], v[94:95], v[208:209]
	v_pk_mul_f32 v[90:91], v[90:91], v[204:205]
	v_pk_mul_f32 v[86:87], v[86:87], v[200:201]
	v_pk_mul_f32 v[82:83], v[82:83], v[196:197]
	v_pk_mul_f32 v[80:81], v[80:81], v[194:195]
	v_pk_mul_f32 v[76:77], v[76:77], v[206:207]
	v_pk_mul_f32 v[72:73], v[72:73], v[202:203]
	v_pk_mul_f32 v[68:69], v[68:69], v[198:199]
	v_pk_mul_f32 v[78:79], v[78:79], v[208:209]
	v_pk_mul_f32 v[74:75], v[74:75], v[204:205]
	v_pk_mul_f32 v[70:71], v[70:71], v[200:201]
	v_pk_mul_f32 v[66:67], v[66:67], v[196:197]
	v_pk_mul_f32 v[64:65], v[64:65], v[194:195]
	v_pk_mul_f32 v[60:61], v[60:61], v[206:207]
	v_pk_mul_f32 v[56:57], v[56:57], v[202:203]
	v_pk_mul_f32 v[52:53], v[52:53], v[198:199]
	v_pk_mul_f32 v[62:63], v[62:63], v[208:209]
	v_pk_mul_f32 v[58:59], v[58:59], v[204:205]
	v_pk_mul_f32 v[54:55], v[54:55], v[200:201]
	v_pk_mul_f32 v[50:51], v[50:51], v[196:197]
	v_pk_mul_f32 v[48:49], v[48:49], v[194:195]
	v_pk_mul_f32 v[44:45], v[44:45], v[206:207]
	v_pk_mul_f32 v[40:41], v[40:41], v[202:203]
	v_pk_mul_f32 v[36:37], v[36:37], v[198:199]
	v_pk_mul_f32 v[46:47], v[46:47], v[208:209]
	v_pk_mul_f32 v[42:43], v[42:43], v[204:205]
	v_pk_mul_f32 v[38:39], v[38:39], v[200:201]
	v_pk_mul_f32 v[34:35], v[34:35], v[196:197]
	v_pk_mul_f32 v[32:33], v[32:33], v[194:195]
	v_pk_mul_f32 v[28:29], v[28:29], v[206:207]
	v_pk_mul_f32 v[24:25], v[24:25], v[202:203]
	v_pk_mul_f32 v[20:21], v[20:21], v[198:199]
	v_pk_mul_f32 v[30:31], v[30:31], v[208:209]
	v_pk_mul_f32 v[26:27], v[26:27], v[204:205]
	v_pk_mul_f32 v[22:23], v[22:23], v[200:201]
	v_pk_mul_f32 v[18:19], v[18:19], v[196:197]
	v_pk_mul_f32 v[16:17], v[16:17], v[194:195]
	v_pk_mul_f32 v[12:13], v[12:13], v[206:207]
	v_pk_mul_f32 v[8:9], v[8:9], v[202:203]
	v_pk_mul_f32 v[4:5], v[4:5], v[198:199]
	v_pk_mul_f32 v[14:15], v[14:15], v[208:209]
	v_pk_mul_f32 v[10:11], v[10:11], v[204:205]
	v_pk_mul_f32 v[6:7], v[6:7], v[200:201]
	v_pk_mul_f32 v[2:3], v[2:3], v[196:197]
	v_pk_mul_f32 v[0:1], v[0:1], v[194:195]
